# grid-barrier census poll loops: s_sleep 1 removed (3 sites); otherwise v23
# baseline (speedup 1.0000x reference)
.LBB0_29:
	global_load_dword v3, v1, s[80:81] sc1
	s_waitcnt lgkmcnt(0)
	global_load_dword v0, v1, s[48:49] sc1
	global_load_dword v2, v1, s[94:95] sc1
	s_mov_b64 s[6:7], -1
	s_mov_b64 s[20:21], -1
	v_readlane_b32 s2, v251, 15
	v_readlane_b32 s3, v251, 16
	s_nop 1
	v_mov_b32_e32 v148, s2
	v_mov_b32_e32 v149, s3
	global_load_dword v4, v[148:149], off sc1
	v_readlane_b32 s2, v251, 17
	v_readlane_b32 s3, v251, 18
	s_nop 1
	v_mov_b32_e32 v150, s2
	v_mov_b32_e32 v151, s3
	global_load_dword v5, v[150:151], off sc1
	v_readlane_b32 s2, v251, 19
	v_readlane_b32 s3, v251, 20
	s_nop 1
	v_mov_b32_e32 v152, s2
	v_mov_b32_e32 v153, s3
	global_load_dword v6, v[152:153], off sc1
	v_readlane_b32 s2, v251, 21
	v_readlane_b32 s3, v251, 22
	s_nop 1
	v_mov_b32_e32 v154, s2
	v_mov_b32_e32 v155, s3
	global_load_dword v7, v[154:155], off sc1
	v_readlane_b32 s2, v251, 23
	v_readlane_b32 s3, v251, 24
	s_nop 1
	v_mov_b32_e32 v156, s2
	v_mov_b32_e32 v157, s3
	global_load_dword v8, v[156:157], off sc1
	v_readlane_b32 s2, v251, 25
	v_readlane_b32 s3, v251, 26
	s_nop 1
	v_mov_b32_e32 v158, s2
	v_mov_b32_e32 v159, s3
	global_load_dword v9, v[158:159], off sc1
	v_readlane_b32 s2, v251, 27
	v_readlane_b32 s3, v251, 28
	s_nop 1
	v_mov_b32_e32 v160, s2
	v_mov_b32_e32 v161, s3
	global_load_dword v10, v[160:161], off sc1
	v_readlane_b32 s2, v251, 29
	v_readlane_b32 s3, v251, 30
	s_nop 1
	v_mov_b32_e32 v162, s2
	v_mov_b32_e32 v163, s3
	global_load_dword v11, v[162:163], off sc1
	v_readlane_b32 s2, v251, 31
	v_readlane_b32 s3, v251, 32
	s_nop 1
	v_mov_b32_e32 v164, s2
	v_mov_b32_e32 v165, s3
	global_load_dword v12, v[164:165], off sc1
	v_readlane_b32 s2, v251, 33
	v_readlane_b32 s3, v251, 34
	s_nop 1
	v_mov_b32_e32 v166, s2
	v_mov_b32_e32 v167, s3
	global_load_dword v13, v[166:167], off sc1
	v_readlane_b32 s2, v251, 35
	v_readlane_b32 s3, v251, 36
	s_nop 1
	v_mov_b32_e32 v168, s2
	v_mov_b32_e32 v169, s3
	global_load_dword v14, v[168:169], off sc1
	v_readlane_b32 s2, v251, 37
	v_readlane_b32 s3, v251, 38
	s_nop 1
	v_mov_b32_e32 v170, s2
	v_mov_b32_e32 v171, s3
	global_load_dword v15, v[170:171], off sc1
	v_readlane_b32 s2, v251, 39
	v_readlane_b32 s3, v251, 40
	s_nop 1
	v_mov_b32_e32 v172, s2
	v_mov_b32_e32 v173, s3
	global_load_dword v16, v[172:173], off sc1
	s_waitcnt vmcnt(0)
	v_add_u32_e32 v17, v0, v3
	v_add_u32_e32 v17, v17, v2
	v_add_u32_e32 v17, v17, v4
	v_add_u32_e32 v17, v17, v5
	v_add_u32_e32 v17, v17, v6
	v_add_u32_e32 v17, v17, v7
	v_add_u32_e32 v17, v17, v8
	v_add_u32_e32 v17, v17, v9
	v_add_u32_e32 v17, v17, v10
	v_add_u32_e32 v17, v17, v11
	v_add_u32_e32 v17, v17, v12
	v_add_u32_e32 v17, v17, v13
	v_add_u32_e32 v17, v17, v14
	v_add_u32_e32 v17, v17, v15
	v_add_u32_e32 v17, v17, v16
	v_cmp_eq_u32_e32 vcc, s97, v17
	s_cbranch_vccnz .LBB0_28
	s_and_b32 s3, s0, 0xff
	s_cmp_eq_u32 s3, 0
	s_mov_b64 s[22:23], -1
	s_cbranch_scc1 .LBB0_33
	s_and_b64 vcc, exec, s[22:23]
	s_cbranch_vccz .LBB0_28

.LBB0_47:
	s_and_b32 s3, s0, 0xff
	s_mov_b64 s[40:41], -1
	s_cmp_lg_u32 s3, 0
	s_mov_b64 s[44:45], -1
	s_cbranch_scc0 .LBB0_50
	s_and_b64 vcc, exec, s[44:45]
	s_cbranch_vccz .LBB0_46
